# C mixer loop rewritten: ALiBi bias folded into QK accumulator init, first half of exp/sum/cvt overlapped with second half of PV MFMAs (mid-PV skip/rescale decision)
# speedup vs baseline: 1.0124x; 1.0093x over previous
; __device__ __forceinline__ unsigned cvtpk(float lo, float hi) { f32x2 v = {lo, hi}; bf16x2_t b = __builtin_convertvector(v, bf16x2_t); return __builtin_bit_cast(unsigned, b); }
; __device__ __forceinline__ void attn_C_item(const bf16_t* P, bf16_t* act_c, int S, int seqbase, int q0, int h, float lam, float oml, const float* subln_g, LAS char* lds, int tid, int w, int lane) {
;     ...
;                 for (int rg = 0; rg < 16; ++rg) { s0[rg] = __builtin_amdgcn_exp2f(s0[rg]); s1[rg] = __builtin_amdgcn_exp2f(s1[rg]); ps0 += s0[rg]; ps1 += s1[rg]; }
;                 l += ps0 + ps1;
; #pragma unroll
;                 for (int st = 0; st < 2; ++st) {
;                     u32x4 wa, wb;
;                     wa.x = cvtpk(s0[8 * st + 0], s0[8 * st + 1]); wa.y = cvtpk(s0[8 * st + 2], s0[8 * st + 3]); wa.z = cvtpk(s0[8 * st + 4], s0[8 * st + 5]); wa.w = cvtpk(s0[8 * st + 6], s0[8 * st + 7]);
;                     wb.x = cvtpk(s1[8 * st + 0], s1[8 * st + 1]); wb.y = cvtpk(s1[8 * st + 2], s1[8 * st + 3]); wb.z = cvtpk(s1[8 * st + 4], s1[8 * st + 5]); wb.w = cvtpk(s1[8 * st + 6], s1[8 * st + 7]);
;                     pf[st] = __builtin_bit_cast(bf16x8, wa); pf[2 + st] = __builtin_bit_cast(bf16x8, wb);
;                 }
.LBB0_198:
	v_exp_f32_e32 v128, v128
	v_exp_f32_e32 v129, v129
	v_exp_f32_e32 v112, v112
	v_exp_f32_e32 v113, v113
	v_pk_add_f32 v[82:83], v[128:129], 0 op_sel_hi:[1,0]
	v_exp_f32_e32 v130, v130
	v_exp_f32_e32 v131, v131
	v_pk_add_f32 v[82:83], v[112:113], v[82:83]
	v_exp_f32_e32 v114, v114
	v_exp_f32_e32 v115, v115
	v_pk_add_f32 v[82:83], v[130:131], v[82:83]
	v_exp_f32_e32 v132, v132
	v_exp_f32_e32 v133, v133
	v_pk_add_f32 v[82:83], v[114:115], v[82:83]
	v_exp_f32_e32 v116, v116
	v_exp_f32_e32 v117, v117
	v_pk_add_f32 v[82:83], v[132:133], v[82:83]
	v_exp_f32_e32 v134, v134
	v_exp_f32_e32 v135, v135
	v_pk_add_f32 v[82:83], v[116:117], v[82:83]
	v_exp_f32_e32 v118, v118
	v_exp_f32_e32 v119, v119
	v_pk_add_f32 v[82:83], v[134:135], v[82:83]
	v_exp_f32_e32 v136, v136
	v_exp_f32_e32 v137, v137
	v_pk_add_f32 v[82:83], v[118:119], v[82:83]
	v_exp_f32_e32 v120, v120
	v_exp_f32_e32 v121, v121
	v_pk_add_f32 v[82:83], v[136:137], v[82:83]
	v_exp_f32_e32 v138, v138
	v_exp_f32_e32 v139, v139
	v_pk_add_f32 v[82:83], v[120:121], v[82:83]
	v_exp_f32_e32 v122, v122
	v_exp_f32_e32 v123, v123
	v_pk_add_f32 v[82:83], v[138:139], v[82:83]
	v_exp_f32_e32 v140, v140
	v_exp_f32_e32 v141, v141
	v_pk_add_f32 v[82:83], v[122:123], v[82:83]
	v_exp_f32_e32 v124, v124
	v_exp_f32_e32 v125, v125
	v_pk_add_f32 v[82:83], v[140:141], v[82:83]
	v_exp_f32_e32 v142, v142
	v_exp_f32_e32 v143, v143
	v_pk_add_f32 v[82:83], v[124:125], v[82:83]
	v_exp_f32_e32 v126, v126
	v_exp_f32_e32 v127, v127
	v_pk_add_f32 v[82:83], v[142:143], v[82:83]
	v_cvt_pk_bf16_f32 v172, v128, v129
	v_pk_add_f32 v[82:83], v[126:127], v[82:83]
	v_cvt_pk_bf16_f32 v173, v130, v131
	v_cvt_pk_bf16_f32 v174, v132, v133
	v_add_f32_e32 v82, v82, v83
	v_cvt_pk_bf16_f32 v175, v134, v135
	v_cvt_pk_bf16_f32 v168, v136, v137
	v_add_f32_e32 v205, v205, v82
	v_cvt_pk_bf16_f32 v169, v138, v139
	v_cvt_pk_bf16_f32 v170, v140, v141
	v_cvt_pk_bf16_f32 v171, v142, v143
	v_cvt_pk_bf16_f32 v160, v112, v113
	v_cvt_pk_bf16_f32 v161, v114, v115
	v_cvt_pk_bf16_f32 v162, v116, v117
	v_cvt_pk_bf16_f32 v163, v118, v119
	v_cvt_pk_bf16_f32 v164, v120, v121
	v_cvt_pk_bf16_f32 v165, v122, v123
	v_cvt_pk_bf16_f32 v166, v124, v125
	v_cvt_pk_bf16_f32 v167, v126, v127

; #define LAS __attribute__((address_space(3)))
; #define C_DMA(T, B) do { const size_t ro_ = (size_t)(T) * 64 * 64; const int d_ = (B) * C_BUF; \
;         C_GLDS(k1src + ro_, d_ + w * C_KCS); C_GLDS(k1src + ro_ + (size_t)MC * 64, d_ + C_K2 + w * C_KCS); \
;         C_GLDS(v0src + ro_, d_ + C_V + w * 1024); C_GLDS(v0src + ro_ + (size_t)MC * 64, d_ + C_V + (w + 8) * 1024); } while (0)
; __device__ __forceinline__ void attn_C_item(const bf16_t* P, bf16_t* act_c, int S, int seqbase, int q0, int h, float lam, float oml, const float* subln_g, LAS char* lds, int tid, int w, int lane) {
;     ...
;     auto qk = [&](const LAS char* buf) __attribute__((always_inline)) {
;             s0 = negm; s1 = negm;
;             bf16x8 kfa[4], kfb[4];
; #pragma unroll
;             for (int ks = 0; ks < 4; ++ks) { const int co = ((2 * ks + hh) ^ ksw) << 4; kfa[ks] = *(const LAS bf16x8*)(buf + kroff + co); kfb[ks] = *(const LAS bf16x8*)(buf + kroff + co + 4096); }
;             __builtin_amdgcn_sched_barrier(0);
;             __builtin_amdgcn_s_setprio(1);
; #pragma unroll
;             for (int ks = 0; ks < 4; ++ks) {
;                 s0 = __builtin_amdgcn_mfma_f32_32x32x16_bf16(kfa[ks], qf[ks], s0, 0, 0, 0);
;                 s1 = __builtin_amdgcn_mfma_f32_32x32x16_bf16(kfb[ks], qf[ks], s1, 0, 0, 0);
;             }
;             __builtin_amdgcn_s_setprio(0);
;             __builtin_amdgcn_sched_barrier(0);
;     };
;     ...
;         if (t + 1 < NT) asm volatile("s_waitcnt vmcnt(4)\n\ts_barrier" ::: "memory"); else asm volatile("s_waitcnt vmcnt(0)\n\ts_barrier" ::: "memory");
;         if (t + 2 < NT) C_DMA(TSEQ(t + 2), (t + 2) & 3);
;         const int T = TSEQ(t);
;         qk((const LAS char*)lds + (t & 3) * C_BUF);
.LBB0_204:
	s_add_i32 s12, s17, 0xfffe8000
	s_and_b32 s12, s12, 0x18000
	v_add_u32_e32 v104, s12, v227
	v_add_u32_e32 v84, v104, v243
	v_add_u32_e32 v92, v104, v244
	v_add_u32_e32 v100, v104, v245
	v_add_u32_e32 v108, v104, v246
	ds_read_b128 v[80:83], v84
	ds_read_b128 v[84:87], v84 offset:4096
	ds_read_b128 v[88:91], v92
	ds_read_b128 v[92:95], v92 offset:4096
	ds_read_b128 v[96:99], v100
	ds_read_b128 v[100:103], v100 offset:4096
	ds_read_b128 v[104:107], v108
	ds_read_b128 v[108:111], v108 offset:4096
	s_add_i32 s22, s51, 3
	s_add_i32 s21, s49, s51
	s_add_i32 s12, s21, 3
	s_xor_b64 s[18:19], s[18:19], -1
	s_add_i32 s51, s51, 1
	s_add_i32 s21, s21, 1
	s_add_i32 s13, s20, 2
	s_cmp_lt_i32 s51, s50
	s_cselect_b32 s21, s21, s13
	v_readfirstlane_b32 s100, v206
	v_lshl_or_b32 v183, s21, 6, v178
	s_lshl_b32 s101, s21, 6
	s_sub_i32 s101, s100, s101
	v_sub_u32_e32 v185, v206, v183
	s_add_i32 s13, s101, 31
	v_cvt_f32_i32_e32 v185, v185
	s_cmp_lt_u32 s13, 0x5f
	s_cbranch_scc1 .Lc_cinit_diag
	s_cmp_lt_i32 s101, 0
	s_cselect_b32 s13, 0x80000000, 0
	v_xor_b32_e32 v207, s13, v202
	s_nop 0
	v_fma_f32 v208, v207, v185, v64
	v_fma_f32 v129, -1.0, v207, v208
	v_fma_f32 v112, s66, v207, v208
	v_fma_f32 v113, s67, v207, v208
	v_fma_f32 v114, s70, v207, v208
	v_fma_f32 v130, s68, v207, v208
	v_fma_f32 v115, s71, v207, v208
	v_fma_f32 v131, s69, v207, v208
	v_fma_f32 v116, s74, v207, v208
	v_fma_f32 v132, s72, v207, v208
	v_fma_f32 v117, s75, v207, v208
	v_fma_f32 v133, s73, v207, v208
	v_fma_f32 v118, s78, v207, v208
	v_fma_f32 v134, s76, v207, v208
	v_fma_f32 v119, s79, v207, v208
	v_fma_f32 v135, s77, v207, v208
	v_fma_f32 v120, s82, v207, v208
	v_fma_f32 v136, s80, v207, v208
	v_fma_f32 v121, s83, v207, v208
	v_fma_f32 v137, s81, v207, v208
	v_fma_f32 v122, s86, v207, v208
	v_fma_f32 v138, s84, v207, v208
	v_fma_f32 v123, s87, v207, v208
	v_fma_f32 v139, s85, v207, v208
	v_fma_f32 v124, s90, v207, v208
	v_fma_f32 v140, s88, v207, v208
	v_fma_f32 v125, s91, v207, v208
	v_fma_f32 v141, s89, v207, v208
	v_fma_f32 v126, s94, v207, v208
	v_fma_f32 v142, s92, v207, v208
	v_fma_f32 v127, s95, v207, v208
	v_fma_f32 v143, s93, v207, v208
	v_mov_b32_e32 v128, v208
	s_branch .Lc_cinit_done
.Lc_cinit_diag:
	v_add_f32_e32 v207, -1.0, v185
	v_fma_f32 v128, v202, |v185|, v64
	v_fma_f32 v129, v202, |v207|, v64
	v_add_f32_e64 v207, v185, s66
	v_add_f32_e64 v208, v185, s67
	v_fma_f32 v112, v202, |v207|, v64
	v_fma_f32 v113, v202, |v208|, v64
	v_add_f32_e64 v207, v185, s70
	v_add_f32_e64 v208, v185, s68
	v_fma_f32 v114, v202, |v207|, v64
	v_fma_f32 v130, v202, |v208|, v64
	v_add_f32_e64 v207, v185, s71
	v_add_f32_e64 v208, v185, s69
	v_fma_f32 v115, v202, |v207|, v64
	v_fma_f32 v131, v202, |v208|, v64
	v_add_f32_e64 v207, v185, s74
	v_add_f32_e64 v208, v185, s72
	v_fma_f32 v116, v202, |v207|, v64
	v_fma_f32 v132, v202, |v208|, v64
	v_add_f32_e64 v207, v185, s75
	v_add_f32_e64 v208, v185, s73
	v_fma_f32 v117, v202, |v207|, v64
	v_fma_f32 v133, v202, |v208|, v64
	v_add_f32_e64 v207, v185, s78
	v_add_f32_e64 v208, v185, s76
	v_fma_f32 v118, v202, |v207|, v64
	v_fma_f32 v134, v202, |v208|, v64
	v_add_f32_e64 v207, v185, s79
	v_add_f32_e64 v208, v185, s77
	v_fma_f32 v119, v202, |v207|, v64
	v_fma_f32 v135, v202, |v208|, v64
	v_add_f32_e64 v207, v185, s82
	v_add_f32_e64 v208, v185, s80
	v_fma_f32 v120, v202, |v207|, v64
	v_fma_f32 v136, v202, |v208|, v64
	v_add_f32_e64 v207, v185, s83
	v_add_f32_e64 v208, v185, s81
	v_fma_f32 v121, v202, |v207|, v64
	v_fma_f32 v137, v202, |v208|, v64
	v_add_f32_e64 v207, v185, s86
	v_add_f32_e64 v208, v185, s84
	v_fma_f32 v122, v202, |v207|, v64
	v_fma_f32 v138, v202, |v208|, v64
	v_add_f32_e64 v207, v185, s87
	v_add_f32_e64 v208, v185, s85
	v_fma_f32 v123, v202, |v207|, v64
	v_fma_f32 v139, v202, |v208|, v64
	v_add_f32_e64 v207, v185, s90
	v_add_f32_e64 v208, v185, s88
	v_fma_f32 v124, v202, |v207|, v64
	v_fma_f32 v140, v202, |v208|, v64
	v_add_f32_e64 v207, v185, s91
	v_add_f32_e64 v208, v185, s89
	v_fma_f32 v125, v202, |v207|, v64
	v_fma_f32 v141, v202, |v208|, v64
	v_add_f32_e64 v207, v185, s94
	v_add_f32_e64 v208, v185, s92
	v_fma_f32 v126, v202, |v207|, v64
	v_fma_f32 v142, v202, |v208|, v64
	v_add_f32_e64 v207, v185, s95
	v_add_f32_e64 v208, v185, s93
	v_fma_f32 v127, v202, |v207|, v64
	v_fma_f32 v143, v202, |v208|, v64
.Lc_cinit_done:
	s_cmp_lt_u32 s22, s55
	s_cbranch_scc0 .Lc_qk_nodma
	s_cmp_lt_i32 s22, s50
	s_cselect_b32 s12, s12, s20
	s_add_i32 s22, s17, 0xffff8000
	s_and_b32 s22, s22, 0x18000
	s_ashr_i32 s13, s12, 31
	s_mov_b32 s24, m0
	s_add_i32 m0, s22, s39
	s_lshl_b64 s[12:13], s[12:13], 13
	v_lshl_add_u64 v[218:219], v[190:191], 0, s[12:13]
	s_add_i32 s23, s22, s40
	s_bitset1_b32 s22, 14
	s_waitcnt lgkmcnt(7)
	v_mfma_f32_32x32x16_bf16 v[128:143], v[80:83], v[144:147], v[128:143]
	s_waitcnt lgkmcnt(6)
	v_mfma_f32_32x32x16_bf16 v[112:127], v[84:87], v[144:147], v[112:127]
	global_load_lds_dwordx4 v[218:219], off
	s_mov_b32 m0, s23
	v_lshl_add_u64 v[218:219], v[218:219], 0, s[44:45]
	s_add_i32 s23, s22, s39
	s_waitcnt lgkmcnt(5)
	v_mfma_f32_32x32x16_bf16 v[128:143], v[88:91], v[148:151], v[128:143]
	s_waitcnt lgkmcnt(4)
	v_mfma_f32_32x32x16_bf16 v[112:127], v[92:95], v[148:151], v[112:127]
	global_load_lds_dwordx4 v[218:219], off
	s_mov_b32 m0, s23
	v_lshl_add_u64 v[218:219], v[200:201], 0, s[12:13]
	s_add_i32 s23, s22, s40
	s_waitcnt lgkmcnt(3)
	v_mfma_f32_32x32x16_bf16 v[128:143], v[96:99], v[152:155], v[128:143]
	s_waitcnt lgkmcnt(2)
	v_mfma_f32_32x32x16_bf16 v[112:127], v[100:103], v[152:155], v[112:127]
	global_load_lds_dwordx4 v[218:219], off
	s_mov_b32 m0, s23
	v_lshl_add_u64 v[218:219], v[218:219], 0, s[44:45]
	s_waitcnt lgkmcnt(1)
	v_mfma_f32_32x32x16_bf16 v[128:143], v[104:107], v[156:159], v[128:143]
	s_waitcnt lgkmcnt(0)
	v_mfma_f32_32x32x16_bf16 v[112:127], v[108:111], v[156:159], v[112:127]
	global_load_lds_dwordx4 v[218:219], off
	s_mov_b32 m0, s24
	s_branch .Lc_qk_done
; #define LAS __attribute__((address_space(3)))
; #define PV_RD(ST, SET) do { _Pragma("unroll") for (int db = 0; db < 4; ++db) { const LAS char* p = vt + (db * 4 + (ST)) * 1024; vlo[SET][db] = vtr(p); vhi[SET][db] = vtr(p + 512); } } while (0)
; #define PV_MM(ST, SET) do { _Pragma("unroll") for (int db = 0; db < 4; ++db) { const bf16x8 vf = {vlo[SET][db][0], vlo[SET][db][1], vlo[SET][db][2], vlo[SET][db][3], vhi[SET][db][0], vhi[SET][db][1], vhi[SET][db][2], vhi[SET][db][3]}; \
;                         o[db] = __builtin_amdgcn_mfma_f32_32x32x16_bf16(vf, pf[ST], o[db], 0, 0, 0); } } while (0)
; __device__ __forceinline__ void attn_C_item(const bf16_t* P, bf16_t* act_c, int S, int seqbase, int q0, int h, float lam, float oml, const float* subln_g, LAS char* lds, int tid, int w, int lane) {
;     ...
;             { auto rr = __builtin_amdgcn_permlane32_swap(__float_as_uint(rm), __float_as_uint(rm), false, false); rm = fmaxf(__uint_as_float(rr[0]), __uint_as_float(rr[1])); }
;             pvalid = first || !__all(rm < -150.0f);
;             if (pvalid) {
;                 if (first || __any(rm > 8.0f)) {
;     ...
;     auto pv_bm = [&](const LAS char* bufp, const int T) __attribute__((always_inline)) {
;             const LAS char* vt = bufp + C_V + troff;
;             s16x4 vlo[2][4], vhi[2][4];
;     ...
;             __builtin_amdgcn_sched_barrier(0);
;             PV_RD(0, 0); PV_RD(1, 1);
;             C_BIASMAX(T);
;             PV_MM(0, 0); PV_RD(2, 0); PV_MM(1, 1); PV_RD(3, 1); PV_MM(2, 0); PV_MM(3, 1);
;             __builtin_amdgcn_sched_group_barrier(0x100, 16, 0);
; #pragma unroll
;             for (int i = 0; i < 4; ++i) { __builtin_amdgcn_sched_group_barrier(0x008, 1, 0); __builtin_amdgcn_sched_group_barrier(0x002, 6, 0); }
;             __builtin_amdgcn_sched_group_barrier(0x100, 8, 0);
; #pragma unroll
;             for (int i = 0; i < 4; ++i) { __builtin_amdgcn_sched_group_barrier(0x008, 1, 0); __builtin_amdgcn_sched_group_barrier(0x002, 6, 0); }
;             __builtin_amdgcn_sched_group_barrier(0x100, 8, 0);
; #pragma unroll
;             for (int i = 0; i < 8; ++i) { __builtin_amdgcn_sched_group_barrier(0x008, 1, 0); __builtin_amdgcn_sched_group_barrier(0x002, 6, 0); }
;             __builtin_amdgcn_sched_barrier(0);
.Lc_qk_nodma:
	s_waitcnt lgkmcnt(7)
	v_mfma_f32_32x32x16_bf16 v[128:143], v[80:83], v[144:147], v[128:143]
	s_waitcnt lgkmcnt(6)
	v_mfma_f32_32x32x16_bf16 v[112:127], v[84:87], v[144:147], v[112:127]
	s_waitcnt lgkmcnt(5)
	v_mfma_f32_32x32x16_bf16 v[128:143], v[88:91], v[148:151], v[128:143]
	s_waitcnt lgkmcnt(4)
	v_mfma_f32_32x32x16_bf16 v[112:127], v[92:95], v[148:151], v[112:127]
	s_waitcnt lgkmcnt(3)
	v_mfma_f32_32x32x16_bf16 v[128:143], v[96:99], v[152:155], v[128:143]
	s_waitcnt lgkmcnt(2)
	v_mfma_f32_32x32x16_bf16 v[112:127], v[100:103], v[152:155], v[112:127]
	s_waitcnt lgkmcnt(1)
	v_mfma_f32_32x32x16_bf16 v[128:143], v[104:107], v[156:159], v[128:143]
	s_waitcnt lgkmcnt(0)
	v_mfma_f32_32x32x16_bf16 v[112:127], v[108:111], v[156:159], v[112:127]
.Lc_qk_done:
	s_and_b64 vcc, exec, s[18:19]
	s_cbranch_vccz .Lc_pv
	s_nop 7
	s_nop 1
	v_max_f32_e32 v183, v128, v129
	v_max_f32_e32 v207, v112, v113
	v_max3_f32 v183, v183, v130, v131
	v_max3_f32 v207, v207, v114, v115
	v_max3_f32 v183, v183, v132, v133
	v_max3_f32 v207, v207, v116, v117
	v_max3_f32 v183, v183, v134, v135
	v_max3_f32 v207, v207, v118, v119
	v_max3_f32 v183, v183, v136, v137
	v_max3_f32 v207, v207, v120, v121
	v_max3_f32 v183, v183, v138, v139
	v_max3_f32 v207, v207, v122, v123
	v_max3_f32 v183, v183, v140, v141
	v_max3_f32 v207, v207, v124, v125
	v_max3_f32 v183, v183, v142, v143
	v_max3_f32 v207, v207, v126, v127
	v_max_f32_e32 v185, v183, v207
	s_branch .LBB0_212
.Lc_pv:
	s_and_b32 s12, s17, 0x18000
	v_add_u32_e32 v185, s12, v248
	ds_read_b64_tr_b16 v[94:95], v185 offset:16384
	ds_read_b64_tr_b16 v[96:97], v185 offset:16896
	ds_read_b64_tr_b16 v[208:209], v185 offset:20480
	ds_read_b64_tr_b16 v[210:211], v185 offset:20992
	ds_read_b64_tr_b16 v[82:83], v185 offset:24576
	ds_read_b64_tr_b16 v[84:85], v185 offset:25088
	ds_read_b64_tr_b16 v[100:101], v185 offset:28672
	ds_read_b64_tr_b16 v[102:103], v185 offset:29184
	ds_read_b64_tr_b16 v[86:87], v185 offset:17408
	ds_read_b64_tr_b16 v[88:89], v185 offset:17920
	ds_read_b64_tr_b16 v[108:109], v185 offset:21504
	ds_read_b64_tr_b16 v[110:111], v185 offset:22016
	ds_read_b64_tr_b16 v[104:105], v185 offset:25600
	ds_read_b64_tr_b16 v[106:107], v185 offset:26112
	ds_read_b64_tr_b16 v[90:91], v185 offset:29696
	ds_read_b64_tr_b16 v[92:93], v185 offset:30208
	s_waitcnt lgkmcnt(14)
	v_mfma_f32_32x32x16_bf16 v[48:63], v[94:97], v[172:175], v[48:63]
	v_max_f32_e32 v183, v128, v129
	v_max_f32_e32 v207, v112, v113
	s_waitcnt lgkmcnt(12)
	v_mfma_f32_32x32x16_bf16 v[32:47], v[208:211], v[172:175], v[32:47]
	v_max3_f32 v183, v183, v130, v131
	v_max3_f32 v207, v207, v114, v115
	s_waitcnt lgkmcnt(10)
	v_mfma_f32_32x32x16_bf16 v[16:31], v[82:85], v[172:175], v[16:31]
	v_max3_f32 v183, v183, v132, v133
	v_max3_f32 v207, v207, v116, v117
	s_waitcnt lgkmcnt(8)
	v_mfma_f32_32x32x16_bf16 v[0:15], v[100:103], v[172:175], v[0:15]
	v_max3_f32 v183, v183, v134, v135
	v_max3_f32 v207, v207, v118, v119
	ds_read_b64_tr_b16 v[66:67], v185 offset:18432
	ds_read_b64_tr_b16 v[68:69], v185 offset:18944
	ds_read_b64_tr_b16 v[70:71], v185 offset:22528
	ds_read_b64_tr_b16 v[72:73], v185 offset:23040
	ds_read_b64_tr_b16 v[208:209], v185 offset:26624
	ds_read_b64_tr_b16 v[210:211], v185 offset:27136
	ds_read_b64_tr_b16 v[212:213], v185 offset:30720
	ds_read_b64_tr_b16 v[214:215], v185 offset:31232
	s_waitcnt lgkmcnt(14)
	v_mfma_f32_32x32x16_bf16 v[48:63], v[86:89], v[168:171], v[48:63]
	v_max3_f32 v183, v183, v136, v137
	v_max3_f32 v207, v207, v120, v121
	s_waitcnt lgkmcnt(12)
	v_mfma_f32_32x32x16_bf16 v[32:47], v[108:111], v[168:171], v[32:47]
	v_max3_f32 v183, v183, v138, v139
	v_max3_f32 v207, v207, v122, v123
	s_waitcnt lgkmcnt(10)
	v_mfma_f32_32x32x16_bf16 v[16:31], v[104:107], v[168:171], v[16:31]
	v_max3_f32 v183, v183, v140, v141
	v_max3_f32 v207, v207, v124, v125
	s_waitcnt lgkmcnt(8)
	v_mfma_f32_32x32x16_bf16 v[0:15], v[90:93], v[168:171], v[0:15]
	v_max3_f32 v183, v183, v142, v143
	v_max3_f32 v207, v207, v126, v127
	ds_read_b64_tr_b16 v[74:75], v185 offset:19456
	ds_read_b64_tr_b16 v[76:77], v185 offset:19968
	ds_read_b64_tr_b16 v[78:79], v185 offset:23552
	ds_read_b64_tr_b16 v[80:81], v185 offset:24064
	ds_read_b64_tr_b16 v[94:95], v185 offset:27648
	ds_read_b64_tr_b16 v[96:97], v185 offset:28160
	ds_read_b64_tr_b16 v[216:217], v185 offset:31744
	ds_read_b64_tr_b16 v[218:219], v185 offset:32256
	v_max_f32_e32 v185, v183, v207
	v_mov_b32_e32 v183, v185
	s_mov_b32 s12, 0xc3160000
	s_nop 0
	v_permlane32_swap_b32_e32 v185, v183
	s_mov_b32 s13, 0x41000000
	v_max_f32_e32 v65, v185, v183
	s_nop 0
	v_cmp_gt_f32_e32 vcc, s12, v65
	s_cmp_lg_u64 vcc, exec
	s_cselect_b64 s[18:19], -1, 0
	s_cmp_eq_u64 vcc, exec
	s_cbranch_scc1 .Lc_pvB_skip
	v_cmp_lt_f32_e32 vcc, s13, v65
	s_cbranch_vccnz .Lc_pvB_resc
; __device__ __forceinline__ unsigned cvtpk(float lo, float hi) { f32x2 v = {lo, hi}; bf16x2_t b = __builtin_convertvector(v, bf16x2_t); return __builtin_bit_cast(unsigned, b); }
; __device__ __forceinline__ void attn_C_item(const bf16_t* P, bf16_t* act_c, int S, int seqbase, int q0, int h, float lam, float oml, const float* subln_g, LAS char* lds, int tid, int w, int lane) {
;     ...
;                 float ps0 = 0.f, ps1 = 0.f;
; #pragma unroll
;                 for (int rg = 0; rg < 16; ++rg) { s0[rg] = __builtin_amdgcn_exp2f(s0[rg]); s1[rg] = __builtin_amdgcn_exp2f(s1[rg]); ps0 += s0[rg]; ps1 += s1[rg]; }
;                 l += ps0 + ps1;
; #pragma unroll
;                 for (int st = 0; st < 2; ++st) {
;                     u32x4 wa, wb;
;                     wa.x = cvtpk(s0[8 * st + 0], s0[8 * st + 1]); wa.y = cvtpk(s0[8 * st + 2], s0[8 * st + 3]); wa.z = cvtpk(s0[8 * st + 4], s0[8 * st + 5]); wa.w = cvtpk(s0[8 * st + 6], s0[8 * st + 7]);
;                     wb.x = cvtpk(s1[8 * st + 0], s1[8 * st + 1]); wb.y = cvtpk(s1[8 * st + 2], s1[8 * st + 3]); wb.z = cvtpk(s1[8 * st + 4], s1[8 * st + 5]); wb.w = cvtpk(s1[8 * st + 6], s1[8 * st + 7]);
;                     pf[st] = __builtin_bit_cast(bf16x8, wa); pf[2 + st] = __builtin_bit_cast(bf16x8, wb);
;                 }
;     ...
;             __builtin_amdgcn_sched_barrier(0);
;             PV_RD(0, 0); PV_RD(1, 1);
;             C_BIASMAX(T);
;             PV_MM(0, 0); PV_RD(2, 0); PV_MM(1, 1); PV_RD(3, 1); PV_MM(2, 0); PV_MM(3, 1);
;             __builtin_amdgcn_sched_group_barrier(0x100, 16, 0);
; #pragma unroll
;             for (int i = 0; i < 4; ++i) { __builtin_amdgcn_sched_group_barrier(0x008, 1, 0); __builtin_amdgcn_sched_group_barrier(0x002, 6, 0); }
;             __builtin_amdgcn_sched_group_barrier(0x100, 8, 0);
; #pragma unroll
;             for (int i = 0; i < 4; ++i) { __builtin_amdgcn_sched_group_barrier(0x008, 1, 0); __builtin_amdgcn_sched_group_barrier(0x002, 6, 0); }
;             __builtin_amdgcn_sched_group_barrier(0x100, 8, 0);
; #pragma unroll
;             for (int i = 0; i < 8; ++i) { __builtin_amdgcn_sched_group_barrier(0x008, 1, 0); __builtin_amdgcn_sched_group_barrier(0x002, 6, 0); }
;             __builtin_amdgcn_sched_barrier(0);
	s_waitcnt lgkmcnt(14)
	v_mfma_f32_32x32x16_bf16 v[48:63], v[66:69], v[160:163], v[48:63]
	v_exp_f32_e32 v128, v128
	v_exp_f32_e32 v129, v129
	s_waitcnt lgkmcnt(12)
	v_mfma_f32_32x32x16_bf16 v[32:47], v[70:73], v[160:163], v[32:47]
	v_exp_f32_e32 v130, v130
	v_exp_f32_e32 v131, v131
	v_pk_add_f32 v[82:83], v[128:129], 0 op_sel_hi:[1,0]
	s_waitcnt lgkmcnt(10)
	v_mfma_f32_32x32x16_bf16 v[16:31], v[208:211], v[160:163], v[16:31]
	v_exp_f32_e32 v132, v132
	v_exp_f32_e32 v133, v133
	v_pk_add_f32 v[82:83], v[130:131], v[82:83]
	v_cvt_pk_bf16_f32 v172, v128, v129
	s_waitcnt lgkmcnt(8)
	v_mfma_f32_32x32x16_bf16 v[0:15], v[212:215], v[160:163], v[0:15]
	v_exp_f32_e32 v134, v134
	v_exp_f32_e32 v135, v135
	v_pk_add_f32 v[82:83], v[132:133], v[82:83]
	v_cvt_pk_bf16_f32 v173, v130, v131
	s_waitcnt lgkmcnt(6)
	v_mfma_f32_32x32x16_bf16 v[48:63], v[74:77], v[164:167], v[48:63]
	v_exp_f32_e32 v136, v136
	v_exp_f32_e32 v137, v137
	v_pk_add_f32 v[82:83], v[134:135], v[82:83]
	v_cvt_pk_bf16_f32 v174, v132, v133
	s_waitcnt lgkmcnt(4)
	v_mfma_f32_32x32x16_bf16 v[32:47], v[78:81], v[164:167], v[32:47]
	v_exp_f32_e32 v138, v138
	v_exp_f32_e32 v139, v139
	v_pk_add_f32 v[82:83], v[136:137], v[82:83]
	v_cvt_pk_bf16_f32 v175, v134, v135
	s_waitcnt lgkmcnt(2)
	v_mfma_f32_32x32x16_bf16 v[16:31], v[94:97], v[164:167], v[16:31]
	v_exp_f32_e32 v140, v140
	v_exp_f32_e32 v141, v141
	v_pk_add_f32 v[82:83], v[138:139], v[82:83]
	v_cvt_pk_bf16_f32 v168, v136, v137
	s_waitcnt lgkmcnt(0)
	v_mfma_f32_32x32x16_bf16 v[0:15], v[216:219], v[164:167], v[0:15]
	v_exp_f32_e32 v142, v142
	v_exp_f32_e32 v143, v143
	v_pk_add_f32 v[82:83], v[140:141], v[82:83]
	v_cvt_pk_bf16_f32 v169, v138, v139
	v_cvt_pk_bf16_f32 v170, v140, v141
	v_pk_add_f32 v[82:83], v[142:143], v[82:83]
	v_exp_f32_e32 v112, v112
	v_exp_f32_e32 v113, v113
	v_cvt_pk_bf16_f32 v171, v142, v143
	v_exp_f32_e32 v114, v114
	v_exp_f32_e32 v115, v115
	v_pk_add_f32 v[82:83], v[112:113], v[82:83]
	v_exp_f32_e32 v116, v116
	v_exp_f32_e32 v117, v117
	v_pk_add_f32 v[82:83], v[114:115], v[82:83]
	v_cvt_pk_bf16_f32 v160, v112, v113
	v_exp_f32_e32 v118, v118
	v_exp_f32_e32 v119, v119
	v_pk_add_f32 v[82:83], v[116:117], v[82:83]
	v_cvt_pk_bf16_f32 v161, v114, v115
	v_exp_f32_e32 v120, v120
	v_exp_f32_e32 v121, v121
	v_pk_add_f32 v[82:83], v[118:119], v[82:83]
	v_cvt_pk_bf16_f32 v162, v116, v117
	v_exp_f32_e32 v122, v122
	v_exp_f32_e32 v123, v123
	v_pk_add_f32 v[82:83], v[120:121], v[82:83]
	v_cvt_pk_bf16_f32 v163, v118, v119
	v_exp_f32_e32 v124, v124
	v_exp_f32_e32 v125, v125
	v_pk_add_f32 v[82:83], v[122:123], v[82:83]
	v_cvt_pk_bf16_f32 v164, v120, v121
	v_exp_f32_e32 v126, v126
	v_exp_f32_e32 v127, v127
	v_pk_add_f32 v[82:83], v[124:125], v[82:83]
	v_cvt_pk_bf16_f32 v165, v122, v123
	v_cvt_pk_bf16_f32 v166, v124, v125
	v_pk_add_f32 v[82:83], v[126:127], v[82:83]
	v_cvt_pk_bf16_f32 v167, v126, v127
	v_add_f32_e32 v82, v82, v83
	s_nop 0
	v_add_f32_e32 v205, v205, v82
	s_branch .LBB0_199
.Lc_pvB_skip:
	s_waitcnt lgkmcnt(14)
	v_mfma_f32_32x32x16_bf16 v[48:63], v[66:69], v[160:163], v[48:63]
	s_waitcnt lgkmcnt(12)
	v_mfma_f32_32x32x16_bf16 v[32:47], v[70:73], v[160:163], v[32:47]
	s_waitcnt lgkmcnt(10)
	v_mfma_f32_32x32x16_bf16 v[16:31], v[208:211], v[160:163], v[16:31]
	s_waitcnt lgkmcnt(8)
	v_mfma_f32_32x32x16_bf16 v[0:15], v[212:215], v[160:163], v[0:15]
	s_waitcnt lgkmcnt(6)
	v_mfma_f32_32x32x16_bf16 v[48:63], v[74:77], v[164:167], v[48:63]
	s_waitcnt lgkmcnt(4)
	v_mfma_f32_32x32x16_bf16 v[32:47], v[78:81], v[164:167], v[32:47]
	s_waitcnt lgkmcnt(2)
	v_mfma_f32_32x32x16_bf16 v[16:31], v[94:97], v[164:167], v[16:31]
	s_waitcnt lgkmcnt(0)
	v_mfma_f32_32x32x16_bf16 v[0:15], v[216:219], v[164:167], v[0:15]
	s_branch .LBB0_199
; __device__ __forceinline__ void attn_C_item(const bf16_t* P, bf16_t* act_c, int S, int seqbase, int q0, int h, float lam, float oml, const float* subln_g, LAS char* lds, int tid, int w, int lane) {
;     ...
;                 if (first || __any(rm > 8.0f)) {
;                     const float dl = first ? rm : fmaxf(rm, 0.0f); m += dl;
;                     if (!first) { const float alpha = __builtin_amdgcn_exp2f(-dl); l *= alpha;
; #pragma unroll
;                     for (int db = 0; db < 4; ++db) o[db] = o[db] * alpha; }
; #pragma unroll
;                     for (int rg = 0; rg < 16; ++rg) { s0[rg] -= dl; s1[rg] -= dl; negm[rg] = -m; }
.Lc_pvB_resc:
	s_waitcnt lgkmcnt(14)
	v_mfma_f32_32x32x16_bf16 v[48:63], v[66:69], v[160:163], v[48:63]
	s_waitcnt lgkmcnt(12)
	v_mfma_f32_32x32x16_bf16 v[32:47], v[70:73], v[160:163], v[32:47]
	s_waitcnt lgkmcnt(10)
	v_mfma_f32_32x32x16_bf16 v[16:31], v[208:211], v[160:163], v[16:31]
	s_waitcnt lgkmcnt(8)
	v_mfma_f32_32x32x16_bf16 v[0:15], v[212:215], v[160:163], v[0:15]
	s_waitcnt lgkmcnt(6)
	v_mfma_f32_32x32x16_bf16 v[48:63], v[74:77], v[164:167], v[48:63]
	s_waitcnt lgkmcnt(4)
	v_mfma_f32_32x32x16_bf16 v[32:47], v[78:81], v[164:167], v[32:47]
	s_waitcnt lgkmcnt(2)
	v_mfma_f32_32x32x16_bf16 v[16:31], v[94:97], v[164:167], v[16:31]
	s_waitcnt lgkmcnt(0)
	v_mfma_f32_32x32x16_bf16 v[0:15], v[216:219], v[164:167], v[0:15]
	v_mov_b32_e32 v80, v65
	s_branch .Lc_resc
.LBB0_212:
	s_nop 4
	v_mov_b32_e32 v80, v185
	s_nop 1
	v_permlane32_swap_b32_e32 v185, v80
	s_mov_b32 s12, 0xc3160000
	v_max_f32_e32 v80, v185, v80
	s_nop 0
	v_cmp_gt_f32_e32 vcc, s12, v80
	s_cmp_lg_u64 vcc, exec
	s_cselect_b64 s[18:19], -1, 0
	s_cmp_eq_u64 vcc, exec
	s_cbranch_scc1 .LBB0_199
	s_mov_b32 s12, 0x41000000
	v_cmp_lt_f32_e32 vcc, s12, v80
	s_cbranch_vccz .LBB0_198
	s_branch .Lc_resc
.Lc_resc:
	v_max_f32_e32 v65, 0, v80
	v_exp_f32_e64 v64, -v65
	v_add_f32_e32 v204, v204, v65
	v_sub_f32_e32 v128, v128, v65
	v_sub_f32_e32 v112, v112, v65
	v_sub_f32_e32 v129, v129, v65
	v_sub_f32_e32 v113, v113, v65
	v_sub_f32_e32 v130, v130, v65
	v_sub_f32_e32 v114, v114, v65
	v_sub_f32_e32 v131, v131, v65
	v_sub_f32_e32 v115, v115, v65
	v_sub_f32_e32 v132, v132, v65
	v_sub_f32_e32 v116, v116, v65
	v_sub_f32_e32 v133, v133, v65
	v_sub_f32_e32 v117, v117, v65
	v_sub_f32_e32 v134, v134, v65
	v_sub_f32_e32 v118, v118, v65
	v_sub_f32_e32 v135, v135, v65
	v_sub_f32_e32 v119, v119, v65
	v_sub_f32_e32 v136, v136, v65
	v_sub_f32_e32 v120, v120, v65
	v_sub_f32_e32 v137, v137, v65
	v_sub_f32_e32 v121, v121, v65
	v_sub_f32_e32 v138, v138, v65
	v_sub_f32_e32 v122, v122, v65
	v_sub_f32_e32 v139, v139, v65
	v_sub_f32_e32 v123, v123, v65
	v_sub_f32_e32 v140, v140, v65
	v_sub_f32_e32 v124, v124, v65
	v_sub_f32_e32 v141, v141, v65
	v_sub_f32_e32 v125, v125, v65
	v_sub_f32_e32 v142, v142, v65
	v_sub_f32_e32 v126, v126, v65
	v_sub_f32_e32 v143, v143, v65
	v_sub_f32_e32 v127, v127, v65
	v_pk_mul_f32 v[62:63], v[62:63], v[64:65] op_sel_hi:[1,0]
	v_pk_mul_f32 v[60:61], v[60:61], v[64:65] op_sel_hi:[1,0]
	v_pk_mul_f32 v[58:59], v[58:59], v[64:65] op_sel_hi:[1,0]
	v_pk_mul_f32 v[56:57], v[56:57], v[64:65] op_sel_hi:[1,0]
	v_pk_mul_f32 v[54:55], v[54:55], v[64:65] op_sel_hi:[1,0]
	v_pk_mul_f32 v[52:53], v[52:53], v[64:65] op_sel_hi:[1,0]
	v_pk_mul_f32 v[50:51], v[50:51], v[64:65] op_sel_hi:[1,0]
	v_pk_mul_f32 v[48:49], v[48:49], v[64:65] op_sel_hi:[1,0]
	v_pk_mul_f32 v[46:47], v[46:47], v[64:65] op_sel_hi:[1,0]
	v_pk_mul_f32 v[44:45], v[44:45], v[64:65] op_sel_hi:[1,0]
	v_pk_mul_f32 v[42:43], v[42:43], v[64:65] op_sel_hi:[1,0]
	v_pk_mul_f32 v[40:41], v[40:41], v[64:65] op_sel_hi:[1,0]
	v_pk_mul_f32 v[38:39], v[38:39], v[64:65] op_sel_hi:[1,0]
	v_pk_mul_f32 v[36:37], v[36:37], v[64:65] op_sel_hi:[1,0]
	v_pk_mul_f32 v[34:35], v[34:35], v[64:65] op_sel_hi:[1,0]
	v_pk_mul_f32 v[32:33], v[32:33], v[64:65] op_sel_hi:[1,0]
	v_pk_mul_f32 v[30:31], v[30:31], v[64:65] op_sel_hi:[1,0]
	v_pk_mul_f32 v[28:29], v[28:29], v[64:65] op_sel_hi:[1,0]
	v_pk_mul_f32 v[26:27], v[26:27], v[64:65] op_sel_hi:[1,0]
	v_pk_mul_f32 v[24:25], v[24:25], v[64:65] op_sel_hi:[1,0]
	v_pk_mul_f32 v[22:23], v[22:23], v[64:65] op_sel_hi:[1,0]
	v_pk_mul_f32 v[20:21], v[20:21], v[64:65] op_sel_hi:[1,0]
	v_pk_mul_f32 v[18:19], v[18:19], v[64:65] op_sel_hi:[1,0]
	v_pk_mul_f32 v[16:17], v[16:17], v[64:65] op_sel_hi:[1,0]
	v_pk_mul_f32 v[14:15], v[14:15], v[64:65] op_sel_hi:[1,0]
	v_pk_mul_f32 v[12:13], v[12:13], v[64:65] op_sel_hi:[1,0]
	v_pk_mul_f32 v[10:11], v[10:11], v[64:65] op_sel_hi:[1,0]
	v_pk_mul_f32 v[8:9], v[8:9], v[64:65] op_sel_hi:[1,0]
	v_pk_mul_f32 v[6:7], v[6:7], v[64:65] op_sel_hi:[1,0]
	v_pk_mul_f32 v[4:5], v[4:5], v[64:65] op_sel_hi:[1,0]
	v_pk_mul_f32 v[2:3], v[2:3], v[64:65] op_sel_hi:[1,0]
	v_pk_mul_f32 v[0:1], v[0:1], v[64:65] op_sel_hi:[1,0]
	v_mul_f32_e32 v205, v205, v64
	v_xor_b32_e32 v64, 0x80000000, v204
	s_branch .LBB0_198
